# S5 mixer: workgroup to (batch, group) assignment permuted so the four workgroups sharing each 128-byte line of the S5 input/output columns run on the same XCD
# speedup vs baseline: 1.0006x; 1.0006x over previous
; DI void mix_s5(WVP CP pp, int l, u16* __restrict__ proj, char* smem) {
;   const int BID = get_bid(), GRD = get_grid();
;   const int tid = get_tid(WV), wave = wave_of(tid), lane = tid & 63, h = lane >> 5, l31 = lane & 31;
;   constexpr int RSF = 132;
;   float* buf = (float*)smem + wave * 32 * RSF;
;   float* hend = (float*)(smem + 8 * 32 * RSF * 4);
;   for (int it = BID; it < BATCH * 32; it += GRD) {
;     const int g = it & 31, b = it >> 5;
;     const float* a_re = pp->in[6] + ((size_t)l * 32 + g) * 64;
;     const float* a_im = pp->in[7] + ((size_t)l * 32 + g) * 64;
;     const float dt = __expf(pp->in[8][l * 32 + g]);
;     const float* b_re = pp->in[9] + ((size_t)l * 32 + g) * 64 * 16;
;     const float* b_im = pp->in[10] + ((size_t)l * 32 + g) * 64 * 16;
;     const float* c_re = pp->in[11] + ((size_t)l * 32 + g) * 16 * 64;
;     const float* c_im = pp->in[12] + ((size_t)l * 32 + g) * 16 * 64;
;     const float* dsk = pp->in[13] + (size_t)l * 512 + g * 16;
;     float lr, li;
;     { float ar = a_re[lane], ai = a_im[lane]; float mg = expf(ar * dt); float sn, cs; sincosf(ai * dt, &sn, &cs); lr = mg * cs; li = mg * sn; }
;     bf16x8 bfrag[4];
;     float lam_r[2], lam_i[2];
;     for (int half = 0; half < 2; ++half) {
;       int ps = 32 * half + l31;
;       float ar = a_re[ps], ai = a_im[ps]; float mg = expf(ar * dt); float sn, cs; sincosf(ai * dt, &sn, &cs);
;       lam_r[half] = mg * cs; lam_i[half] = mg * sn;
;       float xr = mg * cs - 1.f, xi = mg * sn, den = 1.f / (ar * ar + ai * ai);
;       float cr = (xr * ar + xi * ai) * den, ci = (xi * ar - xr * ai) * den;
;       float vr[8], vi[8];
;       for (int j = 0; j < 8; ++j) { float br = b_re[ps * 16 + 8 * h + j], bi = b_im[ps * 16 + 8 * h + j]; vr[j] = cr * br - ci * bi; vi[j] = cr * bi + ci * br; }
;       uint4 a = {pack2(vr[0], vr[1]), pack2(vr[2], vr[3]), pack2(vr[4], vr[5]), pack2(vr[6], vr[7])};
;       uint4 c = {pack2(vi[0], vi[1]), pack2(vi[2], vi[3]), pack2(vi[4], vi[5]), pack2(vi[6], vi[7])};
;       bfrag[half] = __builtin_bit_cast(bf16x8, a); bfrag[2 + half] = __builtin_bit_cast(bf16x8, c);
;     }
;     bf16x8 cfrag[4];
;     { int c = lane & 15, kq = lane >> 4;
;       for (int s = 0; s < 4; ++s) {
;         float v[8];
;         for (int j = 0; j < 8; ++j) { int k = 32 * s + 8 * kq + j; v[j] = k < 64 ? c_re[c * 64 + k] : -c_im[c * 64 + k - 64]; }
.LBB0_280:
	s_and_b64 vcc, exec, s[8:9]
	s_cbranch_vccz .LBB0_369
	s_and_b32 s4, s57, 7
	s_lshl_b32 s4, s4, 2
	s_bfe_u32 s5, s57, 0x20003
	s_or_b32 s4, s4, s5
	s_andn2_b32 s5, s57, 31
	s_or_b32 s4, s4, s5
	s_mov_b32 s5, s53
	v_writelane_b32 v255, s26, 45
	v_mbcnt_lo_u32_b32 v0, -1, 0
	v_mbcnt_hi_u32_b32 v0, -1, v0
	s_cmpk_gt_i32 s4, 0xff
	v_add_u32_e32 v2, s3, v0
	v_writelane_b32 v255, s27, 46
	v_readfirstlane_b32 s0, v2
	s_cbranch_scc1 .LBB0_312
	s_ashr_i32 s42, s0, 6
	v_and_b32_e32 v4, 31, v0
	s_mul_i32 s0, s42, 0x4200
	s_add_i32 s10, s0, 0
	v_lshlrev_b32_e32 v3, 2, v4
	v_readlane_b32 s0, v255, 6
	v_and_b32_e32 v9, 15, v0
	v_and_b32_e32 v2, 63, v0
	v_add_u32_e32 v5, s0, v3
	v_readlane_b32 s0, v255, 22
	v_readlane_b32 s1, v255, 23
	s_load_dwordx16 s[16:31], s[0:1], 0x30
	v_readlane_b32 s0, v255, 17
	v_readlane_b32 s1, v255, 18
	s_mov_b32 s8, s0
	s_ashr_i32 s9, s0, 31
	s_lshl_b32 s43, s0, 5
	v_writelane_b32 v255, s0, 17
	s_lshl_b64 s[34:35], s[8:9], 5
	v_bfe_u32 v7, v0, 5, 1
	v_writelane_b32 v255, s1, 18
	s_lshl_b64 s[0:1], s[8:9], 11
	s_waitcnt lgkmcnt(0)
	s_add_u32 s0, s30, s0
	s_addc_u32 s1, s31, s1
	v_bfe_u32 v11, v0, 4, 2
	v_lshlrev_b32_e32 v0, 2, v9
	s_lshl_b32 s44, s42, 9
	v_lshl_add_u64 v[118:119], s[0:1], 0, v[0:1]
	s_ashr_i32 s45, s44, 31
	v_lshlrev_b32_e32 v0, 5, v11
	s_cmp_lt_i32 s42, 7
	v_add_u32_e32 v15, s10, v0
	v_mul_u32_u24_e32 v11, 0x4c00, v11
	v_lshl_or_b32 v0, v9, 8, v0
	s_cselect_b64 s[30:31], -1, 0
	v_lshlrev_b32_e32 v13, 2, v2
	s_cmp_gt_i32 s42, 0
	v_or_b32_e32 v12, v11, v9
	v_mul_u32_u24_e32 v11, 0x840, v7
	v_lshl_add_u64 v[122:123], s[26:27], 0, v[0:1]
	v_lshl_add_u64 v[124:125], s[28:29], 0, v[0:1]
	v_mul_hi_u32_u24_e32 v29, 0x2600, v4
	v_mul_u32_u24_e32 v28, 0x2600, v4
	v_mov_b32_e32 v0, 0x2600
	s_cselect_b64 s[36:37], -1, 0
	v_add_u32_e32 v188, s10, v13
	v_add3_u32 v189, s10, v3, v11
	s_add_u32 s0, s54, 0x4e200
	v_mad_i64_i32 v[28:29], s[10:11], s44, v0, v[28:29]
	v_lshlrev_b32_e32 v0, 4, v7
	v_mul_u32_u24_e32 v120, 0x1300, v4
	s_addc_u32 s1, s55, 0
	s_mul_i32 s12, s42, 0x4c0000
	s_mul_hi_i32 s13, s44, 0x2600
	v_or_b32_e32 v28, v28, v0
	v_lshl_add_u64 v[126:127], s[0:1], 0, v[28:29]
	v_or_b32_e32 v28, s12, v0
	v_mov_b32_e32 v29, s13
	v_lshlrev_b32_e32 v0, 1, v120
	v_lshl_add_u64 v[28:29], v[28:29], 0, v[0:1]
	v_lshl_add_u64 v[128:129], s[0:1], 0, v[28:29]
	s_add_u32 s0, s54, s12
	v_add_u32_e32 v14, 0x1300, v12
	v_lshlrev_b32_e32 v0, 1, v12
	s_addc_u32 s1, s55, s13
	v_add_u32_e32 v16, 0x2600, v12
	v_lshl_add_u64 v[130:131], s[0:1], 0, v[0:1]
	v_lshlrev_b32_e32 v0, 1, v14
	v_add_u32_e32 v18, 0x3900, v12
	v_lshl_add_u64 v[132:133], s[0:1], 0, v[0:1]
	v_lshlrev_b32_e32 v0, 1, v16
	v_add_u32_e32 v20, 0x13000, v12
	v_lshl_add_u64 v[134:135], s[0:1], 0, v[0:1]
	v_lshlrev_b32_e32 v0, 1, v18
	v_add_u32_e32 v22, 0x14300, v12
	v_lshl_add_u64 v[136:137], s[0:1], 0, v[0:1]
	v_lshlrev_b32_e32 v0, 1, v20
	v_lshlrev_b32_e32 v6, 3, v7
	v_add_u32_e32 v24, 0x15600, v12
	v_lshl_add_u64 v[138:139], s[0:1], 0, v[0:1]
	v_lshlrev_b32_e32 v0, 1, v22
	v_lshl_or_b32 v8, v4, 4, v6
	v_add_u32_e32 v26, 0x16900, v12
	v_lshl_add_u64 v[140:141], s[0:1], 0, v[0:1]
	v_lshlrev_b32_e32 v0, 1, v24
	v_or_b32_e32 v10, 0x200, v8
	v_mul_u32_u24_e32 v3, 0x210, v9
	v_readlane_b32 s10, v255, 7
	v_lshl_add_u64 v[142:143], s[0:1], 0, v[0:1]
	v_lshlrev_b32_e32 v0, 1, v26
	v_cmp_gt_u32_e64 s[8:9], 32, v2
	v_xor_b32_e32 v121, 0x80, v13
	v_add_u32_e32 v190, s10, v13
	v_lshl_add_u64 v[144:145], s[0:1], 0, v[0:1]
	v_lshlrev_b32_e32 v191, 2, v2
	v_lshlrev_b32_e32 v0, 2, v4
	v_lshlrev_b32_e32 v192, 2, v8
	v_lshlrev_b32_e32 v193, 2, v10
	v_lshlrev_b32_e32 v146, 1, v6
	v_lshlrev_b32_e32 v206, 1, v12
	v_lshlrev_b32_e32 v207, 1, v14
	v_lshlrev_b32_e32 v208, 1, v16
	v_lshlrev_b32_e32 v209, 1, v18
	v_lshlrev_b32_e32 v210, 1, v20
	v_lshlrev_b32_e32 v211, 1, v22
	v_lshlrev_b32_e32 v212, 1, v24
	v_lshlrev_b32_e32 v213, 1, v26
	v_add_u32_e32 v214, v15, v3
	v_add_u32_e32 v215, s44, v5
	s_mov_b32 s46, s4
	s_branch .LBB0_284
